# combo8 + 12 nop pad after the attention code + K-loop LDS-DMA rebalance 2/5/3/6 (placement variant of combo16)
# speedup vs baseline: 1.0049x; 1.0049x over previous
.LBB0_599:
	s_nop 0
	s_nop 0
	s_nop 0
	s_nop 0
	s_nop 0
	s_nop 0
	s_nop 0
	s_nop 0
	s_nop 0
	s_nop 0
	s_nop 0
	s_nop 0
	s_mov_b32 s8, -1
	s_add_u32 s10, s18, 0x35600000
	v_mbcnt_lo_u32_b32 v0, s8, 0
	v_mbcnt_hi_u32_b32 v0, s8, v0
	v_add_u32_e32 v0, s76, v0
	v_readlane_b32 s8, v254, 25
	v_and_b32_e32 v72, 0xff, v0
	s_addc_u32 s11, s19, 0
	v_add_u32_e32 v35, s8, v0
	v_readfirstlane_b32 s14, v72
	s_mov_b32 s8, 0x80000
	s_mov_b64 s[12:13], -1
	s_cmp_gt_u32 s14, 63
	v_cmp_gt_i32_e64 s[8:9], s8, v35
	s_cbranch_scc0 .LBB0_618
	s_lshr_b32 s14, s14, 6
	s_cmp_lt_i32 s14, 2
	s_cbranch_scc1 .LBB0_612
	s_cmp_lg_u32 s14, 2
	s_cbranch_scc0 .LBB0_606
	s_and_saveexec_b64 s[12:13], s[8:9]
	s_movk_i32 s20, 0x800
	s_movk_i32 s21, 0x7ff
	s_movk_i32 s22, 0x6000
	s_mov_b32 s23, 0xd000
	s_mov_b32 s27, 0x13000
	s_movk_i32 s28, 0x7fe
	s_movk_i32 s34, 0x7fd
	s_mov_b32 s35, 0x77fff
	s_mov_b64 s[42:43], 0x1800
	s_cbranch_execz .LBB0_605
	v_lshlrev_b32_e32 v2, 3, v72
	v_lshlrev_b32_e32 v0, 4, v72
	v_lshl_add_u64 v[68:69], s[10:11], 0, v[0:1]
	s_mov_b64 s[14:15], 0
	v_lshlrev_b32_e32 v0, 1, v2
	v_mov_b32_e32 v73, v35
